# nt cache hint on the once-read f32 KV-cache K/V loads of the sample-attention unit (80 loads), on top of addpart_vm
# baseline (speedup 1.0000x reference)
.LBB0_1066:
	v_mov_b32_e32 v135, v194
	s_mov_b64 s[30:31], s[0:1]
	s_lshr_b32 s56, s82, 6
	s_load_dwordx2 s[28:29], s[30:31], 0xe0
	s_load_dwordx4 s[4:7], s[30:31], 0x10
	s_lshl_b32 s53, s56, 5
	v_and_b32_e32 v137, 31, v135
	s_bitset1_b32 s53, 15
	s_bfe_u32 s57, s82, 0x40002
	v_or_b32_e32 v36, s53, v137
	s_lshl_b32 s12, s56, 22
	s_lshl_b32 s54, s57, 6
	v_lshlrev_b32_e32 v0, 11, v36
	v_readfirstlane_b32 s55, v135
	s_or_b32 s12, s54, s12
	s_waitcnt lgkmcnt(0)
	v_lshl_add_u64 v[2:3], s[28:29], 0, v[0:1]
	s_lshl_b32 s30, s57, 7
	s_mov_b32 s31, s13
	s_ashr_i32 s52, s55, 6
	v_bfe_u32 v146, v135, 5, 1
	v_lshl_add_u64 v[2:3], v[2:3], 0, s[30:31]
	s_mov_b64 s[30:31], 0x4a00000
	s_lshl_b64 s[58:59], s[12:13], 2
	v_lshl_add_u64 v[130:131], v[2:3], 0, s[30:31]
	v_lshlrev_b32_e32 v0, 4, v146
	s_add_u32 s30, s4, s58
	v_lshl_add_u64 v[2:3], v[130:131], 0, v[0:1]
	s_addc_u32 s31, s5, s59
	s_lshl_b32 s4, s52, 9
	global_load_dwordx4 v[62:65], v[2:3], off
	global_load_dwordx4 v[58:61], v[2:3], off offset:32
	global_load_dwordx4 v[54:57], v[2:3], off offset:64
	global_load_dwordx4 v[50:53], v[2:3], off offset:96
	v_or_b32_e32 v2, s4, v137
	v_ashrrev_i32_e32 v3, 31, v2
	v_lshlrev_b32_e32 v148, 2, v146
	v_lshlrev_b64 v[4:5], 12, v[2:3]
	v_or_b32_e32 v140, s4, v148
	v_lshl_add_u64 v[4:5], s[30:31], 0, v[4:5]
	v_and_b32_e32 v0, 32, v135
	v_ashrrev_i32_e32 v141, 31, v140
	v_lshl_add_u64 v[4:5], v[4:5], 0, v[0:1]
	s_add_u32 s6, s6, s58
	v_or_b32_e32 v147, 16, v148
	v_lshlrev_b64 v[6:7], 12, v[140:141]
	v_or_b32_e32 v161, 1, v148
	v_or_b32_e32 v141, 2, v148
	v_or_b32_e32 v149, 3, v148
	v_or_b32_e32 v150, 8, v148
	v_or_b32_e32 v151, 9, v148
	v_or_b32_e32 v152, 10, v148
	v_or_b32_e32 v153, 11, v148
	v_or_b32_e32 v154, 17, v148
	v_or_b32_e32 v155, 18, v148
	v_or_b32_e32 v156, 19, v148
	v_or_b32_e32 v157, 24, v148
	v_or_b32_e32 v158, 25, v148
	v_or_b32_e32 v159, 26, v148
	v_or_b32_e32 v160, 27, v148
	global_load_dwordx4 v[90:93], v[4:5], off offset:16 nt
	global_load_dwordx4 v[94:97], v[4:5], off nt
	global_load_dwordx4 v[82:85], v[4:5], off offset:80 nt
	global_load_dwordx4 v[86:89], v[4:5], off offset:64 nt
	global_load_dwordx4 v[74:77], v[4:5], off offset:144 nt
	global_load_dwordx4 v[78:81], v[4:5], off offset:128 nt
	global_load_dwordx4 v[66:69], v[4:5], off offset:208 nt
	global_load_dwordx4 v[70:73], v[4:5], off offset:192 nt
	s_addc_u32 s7, s7, s59
	v_lshlrev_b32_e32 v132, 2, v137
	v_mov_b32_e32 v133, v1
	v_or_b32_e32 v4, s4, v147
	v_or_b32_e32 v8, s4, v161
	v_or_b32_e32 v10, s4, v141
	v_or_b32_e32 v12, s4, v149
	v_or_b32_e32 v14, s4, v150
	v_or_b32_e32 v16, s4, v151
	v_or_b32_e32 v18, s4, v152
	v_or_b32_e32 v20, s4, v153
	v_or_b32_e32 v22, s4, v154
	v_or_b32_e32 v24, s4, v155
	v_or_b32_e32 v26, s4, v156
	v_or_b32_e32 v28, s4, v157
	v_or_b32_e32 v30, s4, v158
	v_or_b32_e32 v32, s4, v159
	v_or_b32_e32 v34, s4, v160
	v_lshl_add_u64 v[138:139], s[6:7], 0, v[132:133]
	v_ashrrev_i32_e32 v5, 31, v4
	v_ashrrev_i32_e32 v9, 31, v8
	v_ashrrev_i32_e32 v11, 31, v10
	v_ashrrev_i32_e32 v13, 31, v12
	v_ashrrev_i32_e32 v15, 31, v14
	v_ashrrev_i32_e32 v17, 31, v16
	v_ashrrev_i32_e32 v19, 31, v18
	v_ashrrev_i32_e32 v21, 31, v20
	v_ashrrev_i32_e32 v23, 31, v22
	v_ashrrev_i32_e32 v25, 31, v24
	v_ashrrev_i32_e32 v27, 31, v26
	v_ashrrev_i32_e32 v29, 31, v28
	v_ashrrev_i32_e32 v31, 31, v30
	v_ashrrev_i32_e32 v33, 31, v32
	v_ashrrev_i32_e32 v35, 31, v34
	v_lshlrev_b64 v[4:5], 12, v[4:5]
	v_lshl_add_u64 v[6:7], v[138:139], 0, v[6:7]
	v_lshlrev_b64 v[8:9], 12, v[8:9]
	v_lshlrev_b64 v[10:11], 12, v[10:11]
	v_lshlrev_b64 v[12:13], 12, v[12:13]
	v_lshlrev_b64 v[14:15], 12, v[14:15]
	v_lshlrev_b64 v[16:17], 12, v[16:17]
	v_lshlrev_b64 v[18:19], 12, v[18:19]
	v_lshlrev_b64 v[20:21], 12, v[20:21]
	v_lshlrev_b64 v[22:23], 12, v[22:23]
	v_lshlrev_b64 v[24:25], 12, v[24:25]
	v_lshlrev_b64 v[26:27], 12, v[26:27]
	v_lshlrev_b64 v[28:29], 12, v[28:29]
	v_lshlrev_b64 v[30:31], 12, v[30:31]
	v_lshlrev_b64 v[32:33], 12, v[32:33]
	v_lshlrev_b64 v[34:35], 12, v[34:35]
	v_lshl_add_u64 v[8:9], v[138:139], 0, v[8:9]
	v_lshl_add_u64 v[10:11], v[138:139], 0, v[10:11]
	v_lshl_add_u64 v[12:13], v[138:139], 0, v[12:13]
	v_lshl_add_u64 v[14:15], v[138:139], 0, v[14:15]
	v_lshl_add_u64 v[16:17], v[138:139], 0, v[16:17]
	v_lshl_add_u64 v[18:19], v[138:139], 0, v[18:19]
	v_lshl_add_u64 v[20:21], v[138:139], 0, v[20:21]
	v_lshl_add_u64 v[4:5], v[138:139], 0, v[4:5]
	v_lshl_add_u64 v[22:23], v[138:139], 0, v[22:23]
	v_lshl_add_u64 v[24:25], v[138:139], 0, v[24:25]
	v_lshl_add_u64 v[26:27], v[138:139], 0, v[26:27]
	v_lshl_add_u64 v[28:29], v[138:139], 0, v[28:29]
	v_lshl_add_u64 v[30:31], v[138:139], 0, v[30:31]
	v_lshl_add_u64 v[32:33], v[138:139], 0, v[32:33]
	v_lshl_add_u64 v[34:35], v[138:139], 0, v[34:35]
	global_load_dword v181, v[6:7], off nt
	global_load_dword v185, v[8:9], off nt
	global_load_dword v182, v[10:11], off nt
	global_load_dword v186, v[12:13], off nt
	global_load_dword v164, v[12:13], off offset:128 nt
	global_load_dword v165, v[10:11], off offset:128 nt
	global_load_dword v166, v[8:9], off offset:128 nt
	global_load_dword v167, v[6:7], off offset:128 nt
	global_load_dword v183, v[14:15], off nt
	global_load_dword v190, v[16:17], off nt
	global_load_dword v187, v[18:19], off nt
	global_load_dword v191, v[20:21], off nt
	global_load_dword v168, v[20:21], off offset:128 nt
	global_load_dword v169, v[18:19], off offset:128 nt
	global_load_dword v172, v[16:17], off offset:128 nt
	global_load_dword v173, v[14:15], off offset:128 nt
	global_load_dword v180, v[4:5], off nt
	global_load_dword v193, v[22:23], off nt
	global_load_dword v192, v[24:25], off nt
	global_load_dword v205, v[26:27], off nt
	global_load_dword v170, v[26:27], off offset:128 nt
	global_load_dword v171, v[24:25], off offset:128 nt
	global_load_dword v174, v[22:23], off offset:128 nt
	global_load_dword v175, v[4:5], off offset:128 nt
	global_load_dword v184, v[28:29], off nt
	global_load_dword v207, v[30:31], off nt
	global_load_dword v206, v[32:33], off nt
	global_load_dword v208, v[34:35], off nt
	global_load_dword v176, v[34:35], off offset:128 nt
	global_load_dword v177, v[32:33], off offset:128 nt
	global_load_dword v178, v[30:31], off offset:128 nt
	global_load_dword v179, v[28:29], off offset:128 nt
	v_lshl_add_u64 v[142:143], s[30:31], 0, v[0:1]
	s_mul_i32 s12, s56, 0x10200
	s_mul_i32 s30, s57, 0x1020
	s_ashr_i32 s5, s4, 31
	s_add_i32 s12, s12, s30
	s_lshl_b64 s[6:7], s[4:5], 2
	s_lshl_b64 s[30:31], s[12:13], 2
	s_add_u32 s12, s28, s30
	s_addc_u32 s30, s29, s31
	v_lshrrev_b32_e32 v0, 1, v135
	s_add_u32 s6, s12, s6
	v_and_b32_e32 v0, 16, v0
	s_addc_u32 s7, s30, s7
	v_or_b32_e32 v162, 32, v2
	v_lshl_add_u64 v[2:3], s[6:7], 0, v[0:1]
	s_mov_b64 s[6:7], 0x4500040
	v_mov_b32_e32 v100, 0
	v_and_b32_e32 v133, 63, v135
	v_lshlrev_b32_e32 v136, 10, v36
	v_lshlrev_b32_e32 v134, 3, v146
	v_lshl_add_u64 v[144:145], v[2:3], 0, s[6:7]
	v_mov_b32_e32 v114, 0xf149f2ca
	s_mov_b32 s6, 0
	v_mov_b32_e32 v2, 0
	v_mov_b32_e32 v3, v100
	v_mov_b32_e32 v4, v100
	v_mov_b32_e32 v5, v100
	v_mov_b32_e32 v6, v100
	v_mov_b32_e32 v7, v100
	v_mov_b32_e32 v8, v100
	v_mov_b32_e32 v9, v100
	v_mov_b32_e32 v10, v100
	v_mov_b32_e32 v11, v100
	v_mov_b32_e32 v12, v100
	v_mov_b32_e32 v13, v100
	v_mov_b32_e32 v14, v100
	v_mov_b32_e32 v15, v100
	v_mov_b32_e32 v16, v100
	v_mov_b32_e32 v17, v100
	v_mov_b32_e32 v18, 0
	v_mov_b32_e32 v19, v100
	v_mov_b32_e32 v20, v100
	v_mov_b32_e32 v21, v100
	v_mov_b32_e32 v22, v100
	v_mov_b32_e32 v23, v100
	v_mov_b32_e32 v24, v100
	v_mov_b32_e32 v25, v100
	v_mov_b32_e32 v26, v100
	v_mov_b32_e32 v27, v100
	v_mov_b32_e32 v28, v100
	v_mov_b32_e32 v29, v100
	v_mov_b32_e32 v30, v100
	v_mov_b32_e32 v31, v100
	v_mov_b32_e32 v32, v100
	v_mov_b32_e32 v33, v100
.LBB0_1067:
	v_mov_b32_e32 v0, v100
	v_mov_b32_e32 v163, v114
	s_waitcnt vmcnt(0)
	v_cvt_pk_bf16_f32 v114, v94, v95
	v_cvt_pk_bf16_f32 v115, v96, v97
	v_cvt_pk_bf16_f32 v116, v90, v91
	v_cvt_pk_bf16_f32 v117, v92, v93
	v_cvt_pk_bf16_f32 v118, v86, v87
	v_cvt_pk_bf16_f32 v119, v88, v89
	v_cvt_pk_bf16_f32 v120, v82, v83
	v_cvt_pk_bf16_f32 v121, v84, v85
	v_cvt_pk_bf16_f32 v122, v78, v79
	v_cvt_pk_bf16_f32 v123, v80, v81
	v_cvt_pk_bf16_f32 v124, v74, v75
	v_cvt_pk_bf16_f32 v125, v76, v77
	v_cvt_pk_bf16_f32 v126, v70, v71
	v_cvt_pk_bf16_f32 v127, v72, v73
	v_cvt_pk_bf16_f32 v128, v66, v67
	v_cvt_pk_bf16_f32 v129, v68, v69
	v_cvt_pk_bf16_f32 v106, v181, v185
	v_cvt_pk_bf16_f32 v107, v182, v186
	v_cvt_pk_bf16_f32 v108, v183, v190
	v_cvt_pk_bf16_f32 v109, v187, v191
	v_cvt_pk_bf16_f32 v98, v180, v193
	v_cvt_pk_bf16_f32 v99, v192, v205
	v_cvt_pk_bf16_f32 v100, v184, v207
	v_cvt_pk_bf16_f32 v101, v206, v208
	v_cvt_pk_bf16_f32 v110, v167, v166
	v_cvt_pk_bf16_f32 v111, v165, v164
	v_cvt_pk_bf16_f32 v112, v173, v172
	v_cvt_pk_bf16_f32 v113, v169, v168
	v_cvt_pk_bf16_f32 v102, v175, v174
	v_cvt_pk_bf16_f32 v103, v171, v170
	v_cvt_pk_bf16_f32 v104, v179, v178
	v_cvt_pk_bf16_f32 v105, v177, v176
	global_load_dwordx4 v[34:37], v[144:145], off offset:-64
	global_load_dwordx4 v[38:41], v[144:145], off offset:-32
	global_load_dwordx4 v[42:45], v[144:145], off
	global_load_dwordx4 v[46:49], v[144:145], off offset:32
	v_add_u32_e32 v66, s6, v162
	v_add_u32_e32 v69, s6, v140
	v_ashrrev_i32_e32 v67, 31, v66
	v_add_u32_e32 v72, 33, v69
	v_add_u32_e32 v74, 34, v69
	v_add_u32_e32 v76, 35, v69
	v_add_u32_e32 v78, 40, v69
	v_add_u32_e32 v68, 48, v69
	v_add_u32_e32 v70, 32, v69
	v_add_u32_e32 v80, 41, v69
	v_add_u32_e32 v82, 42, v69
	v_add_u32_e32 v84, 43, v69
	v_add_u32_e32 v86, 49, v69
	v_add_u32_e32 v88, 50, v69
	v_add_u32_e32 v90, 51, v69
	v_add_u32_e32 v92, 56, v69
	v_add_u32_e32 v94, 57, v69
	v_add_u32_e32 v96, 58, v69
	v_add_u32_e32 v164, 59, v69
	v_lshlrev_b64 v[66:67], 12, v[66:67]
	v_ashrrev_i32_e32 v73, 31, v72
	v_ashrrev_i32_e32 v75, 31, v74
	v_ashrrev_i32_e32 v77, 31, v76
	v_ashrrev_i32_e32 v79, 31, v78
	v_ashrrev_i32_e32 v69, 31, v68
	v_ashrrev_i32_e32 v71, 31, v70
	v_ashrrev_i32_e32 v81, 31, v80
	v_ashrrev_i32_e32 v83, 31, v82
	v_ashrrev_i32_e32 v85, 31, v84
	v_ashrrev_i32_e32 v87, 31, v86
	v_ashrrev_i32_e32 v89, 31, v88
	v_ashrrev_i32_e32 v91, 31, v90
	v_ashrrev_i32_e32 v93, 31, v92
	v_ashrrev_i32_e32 v95, 31, v94
	v_ashrrev_i32_e32 v97, 31, v96
	v_ashrrev_i32_e32 v165, 31, v164
	v_lshl_add_u64 v[166:167], v[142:143], 0, v[66:67]
	v_lshlrev_b64 v[172:173], 12, v[72:73]
	v_lshlrev_b64 v[174:175], 12, v[74:75]
	v_lshlrev_b64 v[176:177], 12, v[76:77]
	v_lshlrev_b64 v[178:179], 12, v[78:79]
	v_lshlrev_b64 v[168:169], 12, v[68:69]
	v_lshlrev_b64 v[170:171], 12, v[70:71]
	v_lshlrev_b64 v[180:181], 12, v[80:81]
	v_lshlrev_b64 v[182:183], 12, v[82:83]
	v_lshlrev_b64 v[184:185], 12, v[84:85]
	v_lshlrev_b64 v[186:187], 12, v[86:87]
	v_lshlrev_b64 v[190:191], 12, v[88:89]
	v_lshlrev_b64 v[192:193], 12, v[90:91]
	v_lshlrev_b64 v[206:207], 12, v[92:93]
	v_lshlrev_b64 v[208:209], 12, v[94:95]
	v_lshlrev_b64 v[210:211], 12, v[96:97]
	v_lshlrev_b64 v[164:165], 12, v[164:165]
	global_load_dwordx4 v[90:93], v[166:167], off offset:16 nt
	global_load_dwordx4 v[94:97], v[166:167], off nt
	global_load_dwordx4 v[82:85], v[166:167], off offset:80 nt
	global_load_dwordx4 v[86:89], v[166:167], off offset:64 nt
	global_load_dwordx4 v[74:77], v[166:167], off offset:144 nt
	global_load_dwordx4 v[78:81], v[166:167], off offset:128 nt
	global_load_dwordx4 v[66:69], v[166:167], off offset:208 nt
	global_load_dwordx4 v[70:73], v[166:167], off offset:192 nt
	v_lshl_add_u64 v[166:167], v[138:139], 0, v[172:173]
	v_lshl_add_u64 v[172:173], v[138:139], 0, v[174:175]
	v_lshl_add_u64 v[174:175], v[138:139], 0, v[176:177]
	v_lshl_add_u64 v[176:177], v[138:139], 0, v[178:179]
	v_lshl_add_u64 v[170:171], v[138:139], 0, v[170:171]
	v_lshl_add_u64 v[178:179], v[138:139], 0, v[180:181]
	v_lshl_add_u64 v[212:213], v[138:139], 0, v[182:183]
	v_lshl_add_u64 v[216:217], v[138:139], 0, v[184:185]
	v_lshl_add_u64 v[218:219], v[138:139], 0, v[168:169]
	v_lshl_add_u64 v[220:221], v[138:139], 0, v[186:187]
	v_lshl_add_u64 v[226:227], v[138:139], 0, v[206:207]
	v_lshl_add_u64 v[230:231], v[138:139], 0, v[164:165]
	global_load_dword v183, v[176:177], off nt
	global_load_dword v180, v[218:219], off nt
	global_load_dword v184, v[226:227], off nt
	global_load_dword v181, v[170:171], off nt
	global_load_dword v185, v[166:167], off nt
	global_load_dword v182, v[172:173], off nt
	global_load_dword v186, v[174:175], off nt
	global_load_dword v164, v[174:175], off offset:128 nt
	global_load_dword v165, v[172:173], off offset:128 nt
	s_nop 0
	global_load_dword v166, v[166:167], off offset:128 nt
	s_nop 0
	global_load_dword v167, v[170:171], off offset:128 nt
	v_lshl_add_u64 v[228:229], v[138:139], 0, v[208:209]
	v_lshl_add_u64 v[222:223], v[138:139], 0, v[190:191]
	v_lshl_add_u64 v[224:225], v[138:139], 0, v[192:193]
	v_lshl_add_u64 v[210:211], v[138:139], 0, v[210:211]
	global_load_dword v190, v[178:179], off nt
	global_load_dword v187, v[212:213], off nt
	global_load_dword v191, v[216:217], off nt
	global_load_dword v168, v[216:217], off offset:128 nt
	global_load_dword v169, v[212:213], off offset:128 nt
	global_load_dword v172, v[178:179], off offset:128 nt
	global_load_dword v173, v[176:177], off offset:128 nt
	global_load_dword v193, v[220:221], off nt
	global_load_dword v192, v[222:223], off nt
	global_load_dword v205, v[224:225], off nt
	global_load_dword v170, v[224:225], off offset:128 nt
	global_load_dword v171, v[222:223], off offset:128 nt
	global_load_dword v174, v[220:221], off offset:128 nt
	global_load_dword v175, v[218:219], off offset:128 nt
	global_load_dword v207, v[228:229], off nt
	global_load_dword v206, v[210:211], off nt
	global_load_dword v208, v[230:231], off nt
	global_load_dword v176, v[230:231], off offset:128 nt
	global_load_dword v177, v[210:211], off offset:128 nt
	global_load_dword v178, v[228:229], off offset:128 nt
	global_load_dword v179, v[226:227], off offset:128 nt
	s_waitcnt vmcnt(40)
	v_mfma_f32_32x32x16_bf16 v[34:49], v[114:117], v[62:65], v[34:49]
	s_add_i32 s6, s6, 32
	v_lshl_add_u64 v[144:145], v[144:145], 0, s[20:21]
	s_cmpk_eq_i32 s6, 0x1e0
	v_mfma_f32_32x32x16_bf16 v[34:49], v[118:121], v[58:61], v[34:49]
	v_mfma_f32_32x32x16_bf16 v[34:49], v[122:125], v[54:57], v[34:49]
	v_mfma_f32_32x32x16_bf16 v[34:49], v[126:129], v[50:53], v[34:49]
	s_nop 11
	v_max_f32_e32 v114, v35, v35
	v_max_f32_e32 v115, v34, v34
	v_max_f32_e32 v114, v115, v114
	v_max3_f32 v114, v114, v36, v37
	v_max3_f32 v114, v114, v38, v39
	v_max3_f32 v114, v114, v40, v41
	v_max3_f32 v114, v114, v42, v43
	v_max3_f32 v114, v114, v44, v45
	v_max3_f32 v114, v114, v46, v47
	v_max3_f32 v114, v114, v48, v49
	ds_bpermute_b32 v115, v195, v114
	s_waitcnt lgkmcnt(0)
	v_max3_f32 v114, v163, v114, v115
	v_sub_f32_e32 v115, v163, v114
	v_sub_f32_e32 v38, v38, v114
	v_sub_f32_e32 v39, v39, v114
	v_exp_f32_e32 v120, v38
	v_exp_f32_e32 v39, v39
	v_exp_f32_e32 v38, v115
	v_sub_f32_e32 v34, v34, v114
	v_sub_f32_e32 v35, v35, v114
	v_sub_f32_e32 v36, v36, v114
	v_sub_f32_e32 v37, v37, v114
	v_sub_f32_e32 v40, v40, v114
	v_sub_f32_e32 v41, v41, v114
	v_pk_mul_f32 v[16:17], v[16:17], v[38:39] op_sel_hi:[1,0]
	v_pk_mul_f32 v[14:15], v[14:15], v[38:39] op_sel_hi:[1,0]
	v_pk_mul_f32 v[12:13], v[12:13], v[38:39] op_sel_hi:[1,0]
	v_pk_mul_f32 v[10:11], v[10:11], v[38:39] op_sel_hi:[1,0]
	v_pk_mul_f32 v[8:9], v[8:9], v[38:39] op_sel_hi:[1,0]
	v_pk_mul_f32 v[6:7], v[6:7], v[38:39] op_sel_hi:[1,0]
	v_pk_mul_f32 v[4:5], v[4:5], v[38:39] op_sel_hi:[1,0]
	v_pk_mul_f32 v[2:3], v[2:3], v[38:39] op_sel_hi:[1,0]
	v_exp_f32_e32 v116, v34
	v_exp_f32_e32 v117, v35
	v_exp_f32_e32 v118, v36
	v_exp_f32_e32 v119, v37
	v_exp_f32_e32 v40, v40
	v_exp_f32_e32 v41, v41
	v_cvt_pk_bf16_f32 v34, v116, v117
	v_cvt_pk_bf16_f32 v35, v118, v119
	v_cvt_pk_bf16_f32 v36, v120, v39
	v_cvt_pk_bf16_f32 v37, v40, v41
	v_pk_mul_f32 v[32:33], v[32:33], v[38:39] op_sel_hi:[1,0]
	v_mfma_f32_32x32x16_bf16 v[2:17], v[106:109], v[34:37], v[2:17]
	v_mul_f32_e64 v30, v30, v38
	v_mul_f32_e64 v31, v31, v38
	v_mul_f32_e64 v28, v28, v38
	v_mul_f32_e64 v29, v29, v38
	v_mul_f32_e64 v26, v26, v38
	v_mul_f32_e64 v27, v27, v38
	v_pk_mul_f32 v[24:25], v[24:25], v[38:39] op_sel_hi:[1,0]
	v_pk_mul_f32 v[22:23], v[22:23], v[38:39] op_sel_hi:[1,0]
	v_pk_mul_f32 v[20:21], v[20:21], v[38:39] op_sel_hi:[1,0]
	v_pk_mul_f32 v[18:19], v[18:19], v[38:39] op_sel_hi:[1,0]
	v_add_f32_e32 v106, 0, v116
	v_add_f32_e32 v106, v117, v106
	v_mfma_f32_32x32x16_bf16 v[18:33], v[110:113], v[34:37], v[18:33]
	v_sub_f32_e32 v42, v42, v114
	v_sub_f32_e32 v43, v43, v114
	v_sub_f32_e32 v44, v44, v114
	v_sub_f32_e32 v45, v45, v114
	v_sub_f32_e32 v46, v46, v114
	v_sub_f32_e32 v47, v47, v114
	v_sub_f32_e32 v48, v48, v114
	v_sub_f32_e32 v49, v49, v114
	v_add_f32_e32 v106, v118, v106
	v_exp_f32_e32 v42, v42
	v_exp_f32_e32 v43, v43
	v_exp_f32_e32 v44, v44
	v_exp_f32_e32 v45, v45
	v_exp_f32_e32 v46, v46
	v_exp_f32_e32 v47, v47
	v_exp_f32_e32 v48, v48
	v_exp_f32_e32 v49, v49
	v_cvt_pk_bf16_f32 v34, v42, v43
	v_cvt_pk_bf16_f32 v35, v44, v45
	v_cvt_pk_bf16_f32 v36, v46, v47
	v_cvt_pk_bf16_f32 v37, v48, v49
	s_nop 0
	v_mfma_f32_32x32x16_bf16 v[2:17], v[98:101], v[34:37], v[2:17]
	v_add_f32_e32 v98, v119, v106
	v_add_f32_e32 v98, v120, v98
	v_add_f32_e32 v39, v39, v98
	v_add_f32_e32 v39, v40, v39
	v_add_f32_e32 v39, v41, v39
	v_add_f32_e32 v39, v42, v39
	v_add_f32_e32 v39, v43, v39
	v_mfma_f32_32x32x16_bf16 v[18:33], v[102:105], v[34:37], v[18:33]
	v_add_f32_e32 v34, v44, v39
	v_add_f32_e32 v34, v45, v34
	v_add_f32_e32 v34, v46, v34
	v_add_f32_e32 v34, v47, v34
	v_add_f32_e32 v34, v48, v34
	v_add_f32_e32 v100, v49, v34
	v_fmac_f32_e32 v100, v0, v38
	s_cbranch_scc0 .LBB0_1067
	s_lshl_b32 s6, s56, 4
	s_or_b32 s6, s6, s57
	s_mul_i32 s12, s6, 0x1020
	s_lshl_b64 s[6:7], s[12:13], 2
	s_add_u32 s6, s28, s6
	s_addc_u32 s7, s29, s7
	s_add_u32 s6, s6, 0x4500000
	s_addc_u32 s7, s7, 0
	v_lshlrev_b32_e32 v0, 2, v148
	v_lshl_add_u64 v[98:99], s[6:7], 0, v[0:1]
	v_lshl_add_u64 v[34:35], s[4:5], 2, v[98:99]
	s_waitcnt vmcnt(38)
	v_cvt_pk_bf16_f32 v94, v94, v95
	v_cvt_pk_bf16_f32 v95, v96, v97
	v_cvt_pk_bf16_f32 v96, v90, v91
	v_cvt_pk_bf16_f32 v97, v92, v93
	s_waitcnt vmcnt(36)
	v_cvt_pk_bf16_f32 v86, v86, v87
	v_cvt_pk_bf16_f32 v87, v88, v89
	v_cvt_pk_bf16_f32 v88, v82, v83
	v_cvt_pk_bf16_f32 v89, v84, v85
	s_waitcnt vmcnt(34)
	v_cvt_pk_bf16_f32 v82, v78, v79
	v_cvt_pk_bf16_f32 v83, v80, v81
	v_cvt_pk_bf16_f32 v84, v74, v75
	v_cvt_pk_bf16_f32 v85, v76, v77
	s_waitcnt vmcnt(32)
	v_cvt_pk_bf16_f32 v90, v70, v71
	v_cvt_pk_bf16_f32 v91, v72, v73
	v_cvt_pk_bf16_f32 v92, v66, v67
	v_cvt_pk_bf16_f32 v93, v68, v69
	s_waitcnt vmcnt(27)
	v_cvt_pk_bf16_f32 v70, v181, v185
	s_waitcnt vmcnt(25)
	v_cvt_pk_bf16_f32 v71, v182, v186
	s_waitcnt vmcnt(20)
	v_cvt_pk_bf16_f32 v72, v183, v190
	s_waitcnt vmcnt(18)
	v_cvt_pk_bf16_f32 v73, v187, v191
	s_waitcnt vmcnt(13)
	v_cvt_pk_bf16_f32 v66, v180, v193
	s_waitcnt vmcnt(11)
	v_cvt_pk_bf16_f32 v67, v192, v205
	s_waitcnt vmcnt(6)
	v_cvt_pk_bf16_f32 v68, v184, v207
	s_waitcnt vmcnt(4)
	v_cvt_pk_bf16_f32 v69, v206, v208
	v_cvt_pk_bf16_f32 v78, v167, v166
	v_cvt_pk_bf16_f32 v79, v165, v164
	v_cvt_pk_bf16_f32 v80, v173, v172
	v_cvt_pk_bf16_f32 v81, v169, v168
	v_cvt_pk_bf16_f32 v74, v175, v174
	v_cvt_pk_bf16_f32 v75, v171, v170
	s_waitcnt vmcnt(0)
	v_cvt_pk_bf16_f32 v76, v179, v178
	v_cvt_pk_bf16_f32 v77, v177, v176
	global_load_dwordx4 v[46:49], v[34:35], off offset:2016
	global_load_dwordx4 v[42:45], v[34:35], off offset:1984
	global_load_dwordx4 v[38:41], v[34:35], off offset:1952
	s_nop 0
	global_load_dwordx4 v[34:37], v[34:35], off offset:1920
	s_cmp_lt_u32 s55, 64
	s_waitcnt vmcnt(0)
	v_mfma_f32_32x32x16_bf16 v[34:49], v[94:97], v[62:65], v[34:49]
	v_mfma_f32_32x32x16_bf16 v[34:49], v[86:89], v[58:61], v[34:49]
	v_mfma_f32_32x32x16_bf16 v[34:49], v[82:85], v[54:57], v[34:49]
	v_mfma_f32_32x32x16_bf16 v[34:49], v[90:93], v[50:53], v[34:49]
	s_nop 11
	v_max_f32_e32 v0, v35, v35
	v_max_f32_e32 v82, v34, v34
	v_max_f32_e32 v0, v82, v0
	v_max3_f32 v0, v0, v36, v37
	v_max3_f32 v0, v0, v38, v39
	v_max3_f32 v0, v0, v40, v41
	v_max3_f32 v0, v0, v42, v43
	v_max3_f32 v0, v0, v44, v45
	v_max3_f32 v0, v0, v46, v47
	v_max3_f32 v0, v0, v48, v49
	ds_bpermute_b32 v82, v195, v0
	s_waitcnt lgkmcnt(0)
	v_max3_f32 v82, v114, v0, v82
	v_sub_f32_e32 v0, v114, v82
	v_sub_f32_e32 v34, v34, v82
	v_sub_f32_e32 v35, v35, v82
	v_exp_f32_e32 v34, v34
	v_exp_f32_e32 v0, v0
	v_sub_f32_e32 v36, v36, v82
	v_exp_f32_e32 v83, v35
	v_sub_f32_e32 v37, v37, v82
	v_exp_f32_e32 v84, v36
	v_sub_f32_e32 v38, v38, v82
	v_exp_f32_e32 v85, v37
	v_sub_f32_e32 v39, v39, v82
	v_sub_f32_e32 v40, v40, v82
	v_sub_f32_e32 v41, v41, v82
	v_exp_f32_e32 v86, v38
	v_add_f32_e32 v90, 0, v34
	v_pk_mul_f32 v[16:17], v[16:17], v[0:1] op_sel_hi:[1,0]
	v_pk_mul_f32 v[14:15], v[14:15], v[0:1] op_sel_hi:[1,0]
	v_pk_mul_f32 v[12:13], v[12:13], v[0:1] op_sel_hi:[1,0]
	v_pk_mul_f32 v[10:11], v[10:11], v[0:1] op_sel_hi:[1,0]
	v_pk_mul_f32 v[8:9], v[8:9], v[0:1] op_sel_hi:[1,0]
	v_pk_mul_f32 v[6:7], v[6:7], v[0:1] op_sel_hi:[1,0]
	v_pk_mul_f32 v[4:5], v[4:5], v[0:1] op_sel_hi:[1,0]
	v_pk_mul_f32 v[2:3], v[2:3], v[0:1] op_sel_hi:[1,0]
	v_pk_mul_f32 v[32:33], v[32:33], v[0:1] op_sel_hi:[1,0]
	v_pk_mul_f32 v[30:31], v[30:31], v[0:1] op_sel_hi:[1,0]
	v_pk_mul_f32 v[28:29], v[28:29], v[0:1] op_sel_hi:[1,0]
	v_pk_mul_f32 v[26:27], v[26:27], v[0:1] op_sel_hi:[1,0]
	v_pk_mul_f32 v[24:25], v[24:25], v[0:1] op_sel_hi:[1,0]
	v_pk_mul_f32 v[22:23], v[22:23], v[0:1] op_sel_hi:[1,0]
	v_pk_mul_f32 v[20:21], v[20:21], v[0:1] op_sel_hi:[1,0]
	v_pk_mul_f32 v[18:19], v[18:19], v[0:1] op_sel_hi:[1,0]
	v_exp_f32_e32 v87, v39
	v_exp_f32_e32 v88, v40
	v_exp_f32_e32 v89, v41
	v_cvt_pk_bf16_f32 v34, v34, v83
	v_cvt_pk_bf16_f32 v35, v84, v85
	v_cvt_pk_bf16_f32 v36, v86, v87
	v_cvt_pk_bf16_f32 v37, v88, v89
	v_sub_f32_e32 v42, v42, v82
	v_mfma_f32_32x32x16_bf16 v[2:17], v[70:73], v[34:37], v[2:17]
	v_add_f32_e32 v70, v83, v90
	v_sub_f32_e32 v43, v43, v82
	v_exp_f32_e32 v42, v42
	v_sub_f32_e32 v44, v44, v82
	v_exp_f32_e32 v43, v43
	v_sub_f32_e32 v45, v45, v82
	v_exp_f32_e32 v44, v44
	v_mfma_f32_32x32x16_bf16 v[18:33], v[78:81], v[34:37], v[18:33]
	v_add_f32_e32 v34, v84, v70
	v_add_f32_e32 v34, v85, v34
	v_add_f32_e32 v34, v86, v34
	v_add_f32_e32 v34, v87, v34
	v_add_f32_e32 v34, v88, v34
	v_sub_f32_e32 v46, v46, v82
	v_exp_f32_e32 v45, v45
	v_add_f32_e32 v34, v89, v34
	v_sub_f32_e32 v47, v47, v82
	v_sub_f32_e32 v48, v48, v82
	v_sub_f32_e32 v49, v49, v82
	v_exp_f32_e32 v46, v46
	v_add_f32_e32 v34, v42, v34
	v_exp_f32_e32 v47, v47
	v_exp_f32_e32 v48, v48
	v_exp_f32_e32 v49, v49
	v_cvt_pk_bf16_f32 v38, v42, v43
	v_cvt_pk_bf16_f32 v39, v44, v45
	v_cvt_pk_bf16_f32 v40, v46, v47
	v_cvt_pk_bf16_f32 v41, v48, v49
	v_add_f32_e32 v34, v43, v34
	v_mfma_f32_32x32x16_bf16 v[2:17], v[66:69], v[38:41], v[2:17]
	v_add_f32_e32 v34, v44, v34
	v_add_f32_e32 v34, v45, v34
	v_add_f32_e32 v34, v46, v34
	v_add_f32_e32 v34, v47, v34
	v_add_f32_e32 v34, v48, v34
	v_add_f32_e32 v78, v49, v34
	v_fmac_f32_e32 v78, v100, v0
	v_mfma_f32_32x32x16_bf16 v[18:33], v[74:77], v[38:41], v[18:33]
	s_cbranch_scc0 .LBB0_1070
	s_add_u32 s4, s28, 0xcc00000
	v_lshlrev_b32_e32 v0, 1, v136
	s_addc_u32 s5, s29, 0
	v_lshl_add_u64 v[34:35], s[28:29], 0, v[0:1]
	s_lshl_b32 s12, s54, 1
	v_lshl_add_u64 v[34:35], v[34:35], 0, s[12:13]
	v_lshlrev_b32_e32 v0, 1, v134
	v_lshl_add_u64 v[34:35], v[34:35], 0, v[0:1]
	s_mov_b64 s[6:7], 0x8b00000
	v_lshl_add_u64 v[36:37], v[34:35], 0, s[6:7]
	s_mov_b32 s6, 0x8b00000
	v_add_co_u32_e32 v34, vcc, s6, v34
	v_or_b32_e32 v0, s54, v137
	s_nop 0
	v_addc_co_u32_e32 v35, vcc, 0, v35, vcc
	global_load_dwordx4 v[74:77], v[36:37], off offset:32
	global_load_dwordx4 v[70:73], v[36:37], off offset:64
	global_load_dwordx4 v[84:87], v[34:35], off
	global_load_dwordx4 v[66:69], v[36:37], off offset:96
	v_or_b32_e32 v34, s53, v147
	v_lshlrev_b32_e32 v79, 10, v34
	v_or_b32_e32 v34, s53, v148
	v_lshlrev_b32_e32 v80, 10, v34
	v_or_b32_e32 v35, s53, v161
	v_or_b32_e32 v36, s53, v141
	v_or_b32_e32 v37, s53, v149
	v_or_b32_e32 v38, s53, v150
	v_or_b32_e32 v39, s53, v151
	v_or_b32_e32 v40, s53, v152
	v_or_b32_e32 v41, s53, v153
	v_or_b32_e32 v34, v80, v0
	v_lshlrev_b32_e32 v81, 10, v35
	v_lshlrev_b32_e32 v83, 10, v36
	v_lshlrev_b32_e32 v88, 10, v37
	v_lshlrev_b32_e32 v89, 10, v38
	v_lshlrev_b32_e32 v90, 10, v39
	v_lshlrev_b32_e32 v91, 10, v40
	v_lshlrev_b32_e32 v92, 10, v41
	v_lshlrev_b32_e32 v34, 1, v34
	v_or_b32_e32 v35, v81, v0
	v_or_b32_e32 v36, v83, v0
	v_or_b32_e32 v37, v88, v0
	v_or_b32_e32 v38, v89, v0
	v_or_b32_e32 v39, v90, v0
	v_or_b32_e32 v40, v91, v0
	v_or_b32_e32 v41, v92, v0
	v_lshlrev_b32_e32 v35, 1, v35
	v_lshlrev_b32_e32 v36, 1, v36
	v_lshlrev_b32_e32 v37, 1, v37
	v_lshlrev_b32_e32 v38, 1, v38
	v_lshlrev_b32_e32 v39, 1, v39
	v_lshlrev_b32_e32 v40, 1, v40
	v_lshlrev_b32_e32 v41, 1, v41
	global_load_ushort v93, v34, s[4:5]
	global_load_ushort v94, v35, s[4:5]
	global_load_ushort v95, v36, s[4:5]
	global_load_ushort v96, v37, s[4:5]
	global_load_ushort v97, v38, s[4:5]
	global_load_ushort v100, v39, s[4:5]
	global_load_ushort v101, v40, s[4:5]
	global_load_ushort v102, v41, s[4:5]
	v_or_b32_e32 v34, v79, v0
	v_lshlrev_b32_e32 v103, 1, v34
	v_or_b32_e32 v34, s53, v154
	v_lshlrev_b32_e32 v104, 10, v34
	v_or_b32_e32 v34, v104, v0
	v_lshlrev_b32_e32 v105, 1, v34
	v_or_b32_e32 v34, s53, v155
	v_lshlrev_b32_e32 v106, 10, v34
	v_or_b32_e32 v34, v106, v0
	v_lshlrev_b32_e32 v107, 1, v34
	v_or_b32_e32 v34, s53, v156
	v_lshlrev_b32_e32 v108, 10, v34
	v_or_b32_e32 v34, v108, v0
	v_lshlrev_b32_e32 v109, 1, v34
	v_or_b32_e32 v34, s53, v157
	v_lshlrev_b32_e32 v110, 10, v34
	v_or_b32_e32 v34, v110, v0
	v_lshlrev_b32_e32 v111, 1, v34
	v_or_b32_e32 v34, s53, v158
	v_lshlrev_b32_e32 v112, 10, v34
	v_or_b32_e32 v34, v112, v0
	s_mov_b64 s[6:7], 0x4000
	v_lshlrev_b32_e32 v113, 1, v34
	v_or_b32_e32 v34, s53, v159
	v_lshl_add_u64 v[46:47], v[98:99], 0, s[6:7]
	s_movk_i32 s6, 0x4000
	v_lshlrev_b32_e32 v114, 10, v34
	v_add_co_u32_e32 v34, vcc, s6, v98
	v_or_b32_e32 v98, v114, v0
	s_nop 0
	v_addc_co_u32_e32 v35, vcc, 0, v99, vcc
	global_load_dwordx4 v[38:41], v[46:47], off offset:32
	global_load_dwordx4 v[42:45], v[46:47], off offset:64
	s_nop 0
	global_load_dwordx4 v[34:37], v[34:35], off
	s_nop 0
	global_load_dwordx4 v[46:49], v[46:47], off offset:96
	v_or_b32_e32 v99, s53, v160
	v_lshlrev_b32_e32 v99, 10, v99
	v_or_b32_e32 v115, v99, v0
	v_or_b32_e32 v0, 32, v0
	v_or_b32_e32 v80, v80, v0
	v_or_b32_e32 v81, v81, v0
	v_or_b32_e32 v83, v83, v0
	v_or_b32_e32 v88, v88, v0
	v_or_b32_e32 v89, v89, v0
	v_or_b32_e32 v90, v90, v0
	v_or_b32_e32 v91, v91, v0
	v_or_b32_e32 v92, v92, v0
	v_or_b32_e32 v79, v79, v0
	v_or_b32_e32 v104, v104, v0
	v_or_b32_e32 v106, v106, v0
	v_or_b32_e32 v108, v108, v0
	v_or_b32_e32 v110, v110, v0
	v_or_b32_e32 v112, v112, v0
	v_lshlrev_b32_e32 v98, 1, v98
	v_lshlrev_b32_e32 v115, 1, v115
	v_lshlrev_b32_e32 v80, 1, v80
	v_lshlrev_b32_e32 v81, 1, v81
	v_lshlrev_b32_e32 v83, 1, v83
	v_lshlrev_b32_e32 v88, 1, v88
	v_lshlrev_b32_e32 v89, 1, v89
	s_waitcnt vmcnt(0)
	v_mfma_f32_32x32x16_bf16 v[34:49], v[84:87], v[62:65], v[34:49]
	v_or_b32_e32 v62, v114, v0
	v_or_b32_e32 v0, v99, v0
	v_lshlrev_b32_e32 v90, 1, v90
	v_lshlrev_b32_e32 v91, 1, v91
	v_lshlrev_b32_e32 v92, 1, v92
	v_lshlrev_b32_e32 v79, 1, v79
	v_lshlrev_b32_e32 v104, 1, v104
	v_lshlrev_b32_e32 v62, 1, v62
	v_lshlrev_b32_e32 v0, 1, v0
	global_load_ushort v103, v103, s[4:5]
	s_nop 0
	global_load_ushort v105, v105, s[4:5]
	s_nop 0
	global_load_ushort v107, v107, s[4:5]
	s_nop 0
	global_load_ushort v109, v109, s[4:5]
	s_nop 0
	global_load_ushort v111, v111, s[4:5]
	s_nop 0
	global_load_ushort v113, v113, s[4:5]
	s_nop 0
	global_load_ushort v98, v98, s[4:5]
	s_nop 0
	global_load_ushort v115, v115, s[4:5]
	s_nop 0
	global_load_ushort v80, v80, s[4:5]
	s_nop 0
	global_load_ushort v81, v81, s[4:5]
	s_nop 0
	global_load_ushort v83, v83, s[4:5]
	s_nop 0
	global_load_ushort v88, v88, s[4:5]
	s_nop 0
	global_load_ushort v89, v89, s[4:5]
	s_nop 0
	global_load_ushort v90, v90, s[4:5]
	s_nop 0
	global_load_ushort v91, v91, s[4:5]
	s_nop 0
	global_load_ushort v92, v92, s[4:5]
	v_lshlrev_b32_e32 v106, 1, v106
	v_lshlrev_b32_e32 v108, 1, v108
	v_lshlrev_b32_e32 v110, 1, v110
	v_lshlrev_b32_e32 v112, 1, v112
	global_load_ushort v79, v79, s[4:5]
	s_nop 0
	global_load_ushort v84, v104, s[4:5]
	global_load_ushort v85, v106, s[4:5]
	global_load_ushort v86, v108, s[4:5]
	global_load_ushort v87, v110, s[4:5]
	s_nop 0
	global_load_ushort v104, v112, s[4:5]
	v_mfma_f32_32x32x16_bf16 v[34:49], v[74:77], v[58:61], v[34:49]
	global_load_ushort v74, v62, s[4:5]
	s_nop 0
	global_load_ushort v0, v0, s[4:5]
	v_cmp_le_u32_e32 vcc, v148, v137
	v_lshl_or_b32 v58, v94, 16, v93
	v_lshl_or_b32 v59, v96, 16, v95
	v_lshl_or_b32 v60, v100, 16, v97
	v_lshl_or_b32 v61, v102, 16, v101
	s_waitcnt vmcnt(14)
	v_lshl_or_b32 v62, v81, 16, v80
	v_mfma_f32_32x32x16_bf16 v[34:49], v[70:73], v[54:57], v[34:49]
	s_waitcnt vmcnt(12)
	v_lshl_or_b32 v63, v88, 16, v83
	v_lshl_or_b32 v54, v105, 16, v103
	s_waitcnt vmcnt(10)
	v_lshl_or_b32 v64, v90, 16, v89
	s_waitcnt vmcnt(8)
	v_lshl_or_b32 v65, v92, 16, v91
	v_lshl_or_b32 v55, v109, 16, v107
	v_lshl_or_b32 v56, v113, 16, v111
	v_lshl_or_b32 v57, v115, 16, v98
	v_mfma_f32_32x32x16_bf16 v[34:49], v[66:69], v[50:53], v[34:49]
	s_nop 11
	v_cndmask_b32_e32 v50, v203, v34, vcc
	v_cmp_lt_u32_e32 vcc, v148, v137
	s_nop 1
	v_cndmask_b32_e32 v51, v203, v35, vcc
	v_cmp_le_u32_e32 vcc, v141, v137
	v_max_f32_e32 v34, v51, v51
	v_max_f32_e32 v35, v50, v50
	v_cndmask_b32_e32 v52, v203, v36, vcc
	v_cmp_le_u32_e32 vcc, v149, v137
	v_max_f32_e32 v34, v35, v34
	s_waitcnt vmcnt(4)
	v_lshl_or_b32 v35, v86, 16, v85
	v_cndmask_b32_e32 v53, v203, v37, vcc
	v_cmp_le_u32_e32 vcc, v150, v137
	v_max3_f32 v34, v34, v52, v53
	s_waitcnt vmcnt(2)
	v_lshl_or_b32 v36, v104, 16, v87
	v_cndmask_b32_e32 v38, v203, v38, vcc
	v_cmp_le_u32_e32 vcc, v151, v137
	s_nop 1
	v_cndmask_b32_e32 v39, v203, v39, vcc
	v_cmp_le_u32_e32 vcc, v152, v137
	v_max3_f32 v34, v34, v38, v39
	s_nop 0
	v_cndmask_b32_e32 v40, v203, v40, vcc
	v_cmp_le_u32_e32 vcc, v153, v137
	s_nop 1
	v_cndmask_b32_e32 v41, v203, v41, vcc
	v_cmp_le_u32_e32 vcc, v147, v137
	v_max3_f32 v34, v34, v40, v41
	s_nop 0
	v_cndmask_b32_e32 v42, v203, v42, vcc
	v_cmp_le_u32_e32 vcc, v154, v137
	s_nop 1
	v_cndmask_b32_e32 v43, v203, v43, vcc
	v_cmp_le_u32_e32 vcc, v155, v137
	v_max3_f32 v34, v34, v42, v43
	s_nop 0
	v_cndmask_b32_e32 v44, v203, v44, vcc
	v_cmp_le_u32_e32 vcc, v156, v137
	s_nop 1
	v_cndmask_b32_e32 v45, v203, v45, vcc
	v_cmp_le_u32_e32 vcc, v157, v137
	v_max3_f32 v34, v34, v44, v45
	s_nop 0
	v_cndmask_b32_e32 v46, v203, v46, vcc
	v_cmp_le_u32_e32 vcc, v158, v137
	s_nop 1
	v_cndmask_b32_e32 v47, v203, v47, vcc
	v_cmp_le_u32_e32 vcc, v159, v137
	v_max3_f32 v34, v34, v46, v47
	s_nop 0
	v_cndmask_b32_e32 v48, v203, v48, vcc
	v_cmp_le_u32_e32 vcc, v160, v137
	s_nop 1
	v_cndmask_b32_e32 v49, v203, v49, vcc
	v_max3_f32 v37, v34, v48, v49
	ds_bpermute_b32 v66, v195, v37
	v_lshl_or_b32 v34, v84, 16, v79
	s_waitcnt lgkmcnt(0)
	v_max3_f32 v66, v82, v37, v66
	v_sub_f32_e32 v37, v50, v66
	v_exp_f32_e32 v50, v37
	v_sub_f32_e32 v37, v51, v66
	v_exp_f32_e32 v51, v37
	v_sub_f32_e32 v52, v52, v66
	v_exp_f32_e32 v52, v52
	v_sub_f32_e32 v53, v53, v66
	v_exp_f32_e32 v53, v53
	v_sub_f32_e32 v38, v38, v66
	v_add_f32_e32 v67, 0, v50
	v_exp_f32_e32 v68, v38
	v_sub_f32_e32 v38, v39, v66
	v_add_f32_e32 v67, v51, v67
	v_exp_f32_e32 v69, v38
	v_sub_f32_e32 v39, v40, v66
	v_add_f32_e32 v38, v52, v67
	v_exp_f32_e32 v67, v39
	v_sub_f32_e32 v39, v41, v66
	v_add_f32_e32 v38, v53, v38
	v_exp_f32_e32 v41, v39
	v_sub_f32_e32 v39, v42, v66
	v_add_f32_e32 v38, v68, v38
	v_exp_f32_e32 v42, v39
	v_sub_f32_e32 v39, v43, v66
	v_add_f32_e32 v38, v69, v38
	v_exp_f32_e32 v43, v39
	v_add_f32_e32 v38, v67, v38
	v_add_f32_e32 v38, v41, v38
	s_waitcnt vmcnt(0)
	v_lshl_or_b32 v37, v0, 16, v74
	v_sub_f32_e32 v0, v82, v66
	v_add_f32_e32 v38, v42, v38
	v_add_f32_e32 v70, v43, v38
	v_sub_f32_e32 v38, v44, v66
	v_exp_f32_e32 v0, v0
	v_exp_f32_e32 v71, v38
	v_sub_f32_e32 v38, v45, v66
	v_exp_f32_e32 v72, v38
	v_sub_f32_e32 v38, v46, v66
	v_exp_f32_e32 v46, v38
	v_sub_f32_e32 v38, v47, v66
	v_exp_f32_e32 v47, v38
	v_sub_f32_e32 v38, v48, v66
	v_pk_mul_f32 v[16:17], v[16:17], v[0:1] op_sel_hi:[1,0]
	v_pk_mul_f32 v[14:15], v[14:15], v[0:1] op_sel_hi:[1,0]
	v_pk_mul_f32 v[12:13], v[12:13], v[0:1] op_sel_hi:[1,0]
	v_pk_mul_f32 v[10:11], v[10:11], v[0:1] op_sel_hi:[1,0]
	v_pk_mul_f32 v[8:9], v[8:9], v[0:1] op_sel_hi:[1,0]
	v_pk_mul_f32 v[6:7], v[6:7], v[0:1] op_sel_hi:[1,0]
	v_pk_mul_f32 v[4:5], v[4:5], v[0:1] op_sel_hi:[1,0]
	v_pk_mul_f32 v[2:3], v[2:3], v[0:1] op_sel_hi:[1,0]
	v_pk_mul_f32 v[32:33], v[32:33], v[0:1] op_sel_hi:[1,0]
	v_pk_mul_f32 v[30:31], v[30:31], v[0:1] op_sel_hi:[1,0]
	v_pk_mul_f32 v[28:29], v[28:29], v[0:1] op_sel_hi:[1,0]
	v_pk_mul_f32 v[26:27], v[26:27], v[0:1] op_sel_hi:[1,0]
	v_pk_mul_f32 v[24:25], v[24:25], v[0:1] op_sel_hi:[1,0]
	v_pk_mul_f32 v[22:23], v[22:23], v[0:1] op_sel_hi:[1,0]
	v_pk_mul_f32 v[20:21], v[20:21], v[0:1] op_sel_hi:[1,0]
	v_pk_mul_f32 v[18:19], v[18:19], v[0:1] op_sel_hi:[1,0]
	v_exp_f32_e32 v48, v38
	v_cvt_pk_bf16_f32 v38, v50, v51
	v_cvt_pk_bf16_f32 v39, v52, v53
	v_cvt_pk_bf16_f32 v40, v68, v69
	v_cvt_pk_bf16_f32 v41, v67, v41
	v_sub_f32_e32 v44, v49, v66
	v_mfma_f32_32x32x16_bf16 v[2:17], v[58:61], v[38:41], v[2:17]
	v_exp_f32_e32 v49, v44
	v_cvt_pk_bf16_f32 v42, v42, v43
	v_cvt_pk_bf16_f32 v43, v71, v72
	v_cvt_pk_bf16_f32 v44, v46, v47
	v_cvt_pk_bf16_f32 v45, v48, v49
	v_mov_b32_e32 v82, v66
	v_mfma_f32_32x32x16_bf16 v[18:33], v[62:65], v[38:41], v[18:33]
	v_add_f32_e32 v38, v71, v70
	v_add_f32_e32 v38, v72, v38
	v_add_f32_e32 v38, v46, v38
	v_add_f32_e32 v38, v47, v38
	v_add_f32_e32 v38, v48, v38
	v_add_f32_e32 v38, v49, v38
	v_fmac_f32_e32 v38, v78, v0
	v_mfma_f32_32x32x16_bf16 v[2:17], v[54:57], v[42:45], v[2:17]
	v_mov_b32_e32 v78, v38
	v_mfma_f32_32x32x16_bf16 v[18:33], v[34:37], v[42:45], v[18:33]
